# attention chunk loop: K and V^T LDS fragment reads issued 3-4 MFMAs ahead (rotating staging registers) instead of read-wait-MFMA
# speedup vs baseline: 1.0226x; 1.0019x over previous
; #define LAS __attribute__((address_space(3)))
; __device__ void attn_item(const Params& p, int l, int item, LAS unsigned char* lds) {
;     ...
; #pragma unroll
;         for (int kt = 0; kt < 4; ++kt) {
; #pragma unroll
;             for (int r = 0; r < 16; ++r) st[kt][r] = 0.f;
; #pragma unroll
;             for (int ks = 0; ks < 4; ++ks) {
;                 const bf16x8 kf = *(const LAS bf16x8*)(Kl + (32 * kt + l31) * KPITCH + 32 * ks + 16 * hi);
;                 st[kt] = __builtin_amdgcn_mfma_f32_32x32x16_bf16(kf, qf[ks], st[kt], 0, 0, 0);
;             }
;         }
.LBB0_192:
	ds_read_b128 v[32:35], v221
	ds_read_b128 v[36:39], v221 offset:32
	ds_read_b128 v[40:43], v221 offset:64
	ds_read_b128 v[44:47], v221 offset:96
	s_waitcnt lgkmcnt(3)
	v_mfma_f32_32x32x16_bf16 v[80:95], v[32:35], v[98:101], 0
	ds_read_b128 v[32:35], v221 offset:4608
	s_waitcnt lgkmcnt(3)
	v_mfma_f32_32x32x16_bf16 v[80:95], v[36:39], v[102:105], v[80:95]
	ds_read_b128 v[36:39], v221 offset:4640
	s_waitcnt lgkmcnt(3)
	v_mfma_f32_32x32x16_bf16 v[80:95], v[40:43], v[106:109], v[80:95]
	ds_read_b128 v[40:43], v221 offset:4672
	s_waitcnt lgkmcnt(3)
	v_mfma_f32_32x32x16_bf16 v[80:95], v[44:47], v[110:113], v[80:95]
	ds_read_b128 v[44:47], v221 offset:4704
	s_waitcnt lgkmcnt(3)
	v_mfma_f32_32x32x16_bf16 v[64:79], v[32:35], v[98:101], 0
	ds_read_b128 v[32:35], v221 offset:9216
	s_waitcnt lgkmcnt(3)
	v_mfma_f32_32x32x16_bf16 v[64:79], v[36:39], v[102:105], v[64:79]
	ds_read_b128 v[36:39], v221 offset:9248
	s_waitcnt lgkmcnt(3)
	v_mfma_f32_32x32x16_bf16 v[64:79], v[40:43], v[106:109], v[64:79]
	ds_read_b128 v[40:43], v221 offset:9280
	s_waitcnt lgkmcnt(3)
	v_mfma_f32_32x32x16_bf16 v[64:79], v[44:47], v[110:113], v[64:79]
	ds_read_b128 v[44:47], v221 offset:9312
	s_waitcnt lgkmcnt(3)
	v_mfma_f32_32x32x16_bf16 v[48:63], v[32:35], v[98:101], 0
	ds_read_b128 v[32:35], v221 offset:13824
	s_waitcnt lgkmcnt(3)
	v_mfma_f32_32x32x16_bf16 v[48:63], v[36:39], v[102:105], v[48:63]
	ds_read_b128 v[226:229], v221 offset:13856
	s_waitcnt lgkmcnt(3)
	v_mfma_f32_32x32x16_bf16 v[48:63], v[40:43], v[106:109], v[48:63]
	ds_read_b128 v[212:215], v221 offset:13888
	s_waitcnt lgkmcnt(3)
	v_mfma_f32_32x32x16_bf16 v[48:63], v[44:47], v[110:113], v[48:63]
	s_waitcnt lgkmcnt(2)
	v_mfma_f32_32x32x16_bf16 v[32:47], v[32:35], v[98:101], 0
	s_waitcnt lgkmcnt(1)
	v_mfma_f32_32x32x16_bf16 v[32:47], v[226:229], v[102:105], v[32:47]
	ds_read_b128 v[226:229], v221 offset:13920
	s_waitcnt lgkmcnt(1)
	v_mfma_f32_32x32x16_bf16 v[32:47], v[212:215], v[106:109], v[32:47]
	s_waitcnt lgkmcnt(0)
	v_mfma_f32_32x32x16_bf16 v[32:47], v[226:229], v[110:113], v[32:47]
	s_add_i32 s4, s34, -3
	s_cmp_lt_u32 s4, -2
	s_cbranch_scc1 .LBB0_194
	s_cmp_eq_u32 s34, 1
	s_cbranch_scc0 .Lmy_mask2
; __device__ void attn_item(const Params& p, int l, int item, LAS unsigned char* lds) {
;     ...
;         if (mask) {
;             int klo = (mask == 1) ? qq : -1, khi = (mask == 2) ? qq : 1000;
;             asm volatile("" : "+v"(klo), "+v"(khi));
; #pragma unroll
;             for (int kt = 0; kt < 4; ++kt)
; #pragma unroll
;                 for (int r = 0; r < 16; ++r) {
;                     const int kk = 32 * kt + 8 * (r >> 2) + 4 * hi + (r & 3);
;                     st[kt][r] = (kk >= klo && kk <= khi) ? st[kt][r] : -1e30f;
;                 }
;         }
	v_cmp_lt_i32_e32 vcc, v96, v146
	v_cmp_lt_i32_e64 s[40:41], v150, v146
	v_cmp_lt_i32_e64 s[42:43], v151, v146
	v_cndmask_b32_e32 v80, v80, v242, vcc
	v_cmp_lt_i32_e32 vcc, v152, v146
	v_cndmask_b32_e64 v81, v81, v242, s[40:41]
	v_cmp_lt_i32_e64 s[40:41], v153, v146
	v_cndmask_b32_e64 v82, v82, v242, s[42:43]
	v_cmp_lt_i32_e64 s[42:43], v154, v146
	v_cndmask_b32_e32 v83, v83, v242, vcc
	v_cmp_lt_i32_e32 vcc, v155, v146
	v_cndmask_b32_e64 v84, v84, v242, s[40:41]
	v_cmp_lt_i32_e64 s[40:41], v156, v146
	v_cndmask_b32_e64 v85, v85, v242, s[42:43]
	v_cmp_lt_i32_e64 s[42:43], v157, v146
	v_cndmask_b32_e32 v86, v86, v242, vcc
	v_cmp_lt_i32_e32 vcc, v158, v146
	v_cndmask_b32_e64 v87, v87, v242, s[40:41]
	v_cmp_lt_i32_e64 s[40:41], v159, v146
	v_cndmask_b32_e64 v88, v88, v242, s[42:43]
	v_cmp_lt_i32_e64 s[42:43], v160, v146
	v_cndmask_b32_e32 v89, v89, v242, vcc
	v_cmp_lt_i32_e32 vcc, v161, v146
	v_cndmask_b32_e64 v90, v90, v242, s[40:41]
	v_cmp_lt_i32_e64 s[40:41], v162, v146
	v_cndmask_b32_e64 v91, v91, v242, s[42:43]
	v_cmp_lt_i32_e64 s[42:43], v163, v146
	v_cndmask_b32_e32 v92, v92, v242, vcc
	v_cmp_lt_i32_e32 vcc, v164, v146
	v_cndmask_b32_e64 v93, v93, v242, s[40:41]
	v_cmp_lt_i32_e64 s[40:41], v165, v146
	v_cndmask_b32_e64 v94, v94, v242, s[42:43]
	v_cmp_lt_i32_e64 s[42:43], v166, v146
	v_cndmask_b32_e32 v95, v95, v242, vcc
	v_cmp_lt_i32_e32 vcc, v167, v146
	v_cndmask_b32_e64 v64, v64, v242, s[40:41]
	v_cmp_lt_i32_e64 s[40:41], v168, v146
	v_cndmask_b32_e64 v65, v65, v242, s[42:43]
	v_cmp_lt_i32_e64 s[42:43], v169, v146
	v_cndmask_b32_e32 v66, v66, v242, vcc
	v_cmp_lt_i32_e32 vcc, v170, v146
	v_cndmask_b32_e64 v67, v67, v242, s[40:41]
	v_cmp_lt_i32_e64 s[40:41], v171, v146
	v_cndmask_b32_e64 v68, v68, v242, s[42:43]
	v_cmp_lt_i32_e64 s[42:43], v172, v146
	v_cndmask_b32_e32 v69, v69, v242, vcc
	v_cmp_lt_i32_e32 vcc, v173, v146
	v_cndmask_b32_e64 v70, v70, v242, s[40:41]
	v_cmp_lt_i32_e64 s[40:41], v174, v146
	v_cndmask_b32_e64 v71, v71, v242, s[42:43]
	v_cmp_lt_i32_e64 s[42:43], v175, v146
	v_cndmask_b32_e32 v72, v72, v242, vcc
	v_cmp_lt_i32_e32 vcc, v176, v146
	v_cndmask_b32_e64 v73, v73, v242, s[40:41]
	v_cmp_lt_i32_e64 s[40:41], v177, v146
	v_cndmask_b32_e64 v74, v74, v242, s[42:43]
	v_cmp_lt_i32_e64 s[42:43], v178, v146
	v_cndmask_b32_e32 v75, v75, v242, vcc
	v_cmp_lt_i32_e32 vcc, v179, v146
	v_cndmask_b32_e64 v76, v76, v242, s[40:41]
	v_cmp_lt_i32_e64 s[40:41], v180, v146
	v_cndmask_b32_e64 v77, v77, v242, s[42:43]
	v_cmp_lt_i32_e64 s[42:43], v181, v146
	v_cndmask_b32_e32 v78, v78, v242, vcc
	v_cmp_lt_i32_e32 vcc, v182, v146
	v_cndmask_b32_e64 v79, v79, v242, s[40:41]
	v_cmp_lt_i32_e64 s[40:41], v183, v146
	v_cndmask_b32_e64 v48, v48, v242, s[42:43]
	v_cmp_lt_i32_e64 s[42:43], v184, v146
	v_cndmask_b32_e32 v49, v49, v242, vcc
	v_cmp_lt_i32_e32 vcc, v185, v146
	v_cndmask_b32_e64 v50, v50, v242, s[40:41]
	v_cmp_lt_i32_e64 s[40:41], v186, v146
	v_cndmask_b32_e64 v51, v51, v242, s[42:43]
	v_cmp_lt_i32_e64 s[42:43], v187, v146
	v_cndmask_b32_e32 v52, v52, v242, vcc
	v_cmp_lt_i32_e32 vcc, v188, v146
	v_cndmask_b32_e64 v53, v53, v242, s[40:41]
	v_cmp_lt_i32_e64 s[40:41], v189, v146
	v_cndmask_b32_e64 v54, v54, v242, s[42:43]
	v_cmp_lt_i32_e64 s[42:43], v190, v146
	v_cndmask_b32_e32 v55, v55, v242, vcc
	v_cmp_lt_i32_e32 vcc, v191, v146
	v_cndmask_b32_e64 v56, v56, v242, s[40:41]
	v_cmp_lt_i32_e64 s[40:41], v192, v146
	v_cndmask_b32_e64 v57, v57, v242, s[42:43]
	v_cmp_lt_i32_e64 s[42:43], v193, v146
	v_cndmask_b32_e32 v58, v58, v242, vcc
	v_cmp_lt_i32_e32 vcc, v194, v146
	v_cndmask_b32_e64 v59, v59, v242, s[40:41]
	v_cmp_lt_i32_e64 s[40:41], v195, v146
	v_cndmask_b32_e64 v60, v60, v242, s[42:43]
	v_cmp_lt_i32_e64 s[42:43], v196, v146
	v_cndmask_b32_e32 v61, v61, v242, vcc
	v_cmp_lt_i32_e32 vcc, v197, v146
	v_cndmask_b32_e64 v62, v62, v242, s[40:41]
	v_cmp_lt_i32_e64 s[40:41], v198, v146
	v_cndmask_b32_e64 v63, v63, v242, s[42:43]
	v_cmp_lt_i32_e64 s[42:43], v199, v146
	v_cndmask_b32_e32 v32, v32, v242, vcc
	v_cmp_lt_i32_e32 vcc, v200, v146
	v_cndmask_b32_e64 v33, v33, v242, s[40:41]
	v_cmp_lt_i32_e64 s[40:41], v201, v146
	v_cndmask_b32_e64 v34, v34, v242, s[42:43]
	v_cmp_lt_i32_e64 s[42:43], v202, v146
	v_cndmask_b32_e32 v35, v35, v242, vcc
	v_cmp_lt_i32_e32 vcc, v203, v146
	v_cndmask_b32_e64 v36, v36, v242, s[40:41]
	v_cmp_lt_i32_e64 s[40:41], v204, v146
	v_cndmask_b32_e64 v37, v37, v242, s[42:43]
	v_cmp_lt_i32_e64 s[42:43], v205, v146
	v_cndmask_b32_e32 v38, v38, v242, vcc
	v_cmp_lt_i32_e32 vcc, v206, v146
	v_cndmask_b32_e64 v39, v39, v242, s[40:41]
	v_cmp_lt_i32_e64 s[40:41], v207, v146
	v_cndmask_b32_e64 v40, v40, v242, s[42:43]
	v_cmp_lt_i32_e64 s[42:43], v208, v146
	v_cndmask_b32_e32 v41, v41, v242, vcc
	v_cmp_lt_i32_e32 vcc, v209, v146
	v_cndmask_b32_e64 v42, v42, v242, s[40:41]
	v_cmp_lt_i32_e64 s[40:41], v211, v146
	v_cndmask_b32_e64 v43, v43, v242, s[42:43]
	v_cmp_lt_i32_e64 s[42:43], v216, v146
	v_cndmask_b32_e32 v44, v44, v242, vcc
	v_cmp_lt_i32_e32 vcc, v217, v146
	v_cndmask_b32_e64 v45, v45, v242, s[40:41]
	v_cndmask_b32_e64 v46, v46, v242, s[42:43]
	v_cndmask_b32_e32 v47, v47, v242, vcc
	s_branch .LBB0_194

; __device__ void attn_item(const Params& p, int l, int item, LAS unsigned char* lds) {
;     ...
; #pragma unroll
;         for (int kt = 0; kt < 4; ++kt)
; #pragma unroll
;             for (int r = 0; r < 16; ++r) mx = fmaxf(mx, st[kt][r]);
;         mx = fmaxf(mx, __shfl_xor(mx, 32)) * LOG2E;
;         const float mnew = fmaxf(mrun, mx), alpha = __builtin_amdgcn_exp2f(mrun - mnew);
;         float rs = 0.f;
;         __builtin_amdgcn_sched_barrier(0);
; #pragma unroll
;         for (int kt = 0; kt < 4; ++kt)
; #pragma unroll
;             for (int r = 0; r < 16; ++r) { const float e = __builtin_amdgcn_exp2f(fmaf(st[kt][r], LOG2E, -mnew)); st[kt][r] = e; rs += e; }
.LBB0_194:
	s_mov_b32 s4, 0xf149f2ca
	v_max3_f32 v212, v80, s4, v81
	v_max3_f32 v212, v212, v82, v83
	v_max3_f32 v212, v212, v84, v85
	v_max3_f32 v212, v212, v86, v87
	v_max3_f32 v212, v212, v88, v89
	v_max3_f32 v212, v212, v90, v91
	v_max3_f32 v212, v212, v92, v93
	v_max3_f32 v212, v212, v94, v95
	v_max3_f32 v212, v212, v64, v65
	v_max3_f32 v212, v212, v66, v67
	v_max3_f32 v212, v212, v68, v69
	v_max3_f32 v212, v212, v70, v71
	v_max3_f32 v212, v212, v72, v73
	v_max3_f32 v212, v212, v74, v75
	v_max3_f32 v212, v212, v76, v77
	v_max3_f32 v212, v212, v78, v79
	v_max3_f32 v212, v212, v48, v49
	v_max3_f32 v212, v212, v50, v51
	v_max3_f32 v212, v212, v52, v53
	v_max3_f32 v212, v212, v54, v55
	v_max3_f32 v212, v212, v56, v57
	v_max3_f32 v212, v212, v58, v59
	v_max3_f32 v212, v212, v60, v61
	v_max3_f32 v212, v212, v62, v63
	v_max3_f32 v212, v212, v32, v33
	v_max3_f32 v212, v212, v34, v35
	v_max3_f32 v212, v212, v36, v37
	v_max3_f32 v212, v212, v38, v39
	v_and_b32_e32 v214, 64, v236
	v_max3_f32 v212, v212, v40, v41
	v_xor_b32_e32 v213, 32, v236
	v_add_u32_e32 v214, 64, v214
	v_max3_f32 v212, v212, v42, v43
	v_cmp_lt_i32_e32 vcc, v213, v214
	v_max3_f32 v212, v212, v44, v45
	v_max3_f32 v212, v212, v46, v47
	v_cndmask_b32_e32 v213, v236, v213, vcc
	v_lshlrev_b32_e32 v213, 2, v213
	ds_bpermute_b32 v214, v213, v212
	s_waitcnt lgkmcnt(0)
	v_max_f32_e32 v214, v214, v214
	v_max_f32_e32 v212, v212, v214
	v_mul_f32_e32 v212, 0x3fb8aa3b, v212
	v_max_f32_e32 v214, v224, v224
	v_max_f32_e32 v225, v214, v212
	v_sub_f32_e32 v212, v224, v225
	v_fma_f32 v80, v80, s30, -v225
	v_exp_f32_e32 v80, v80
	v_fma_f32 v81, v81, s30, -v225
	v_fma_f32 v82, v82, s30, -v225
	v_exp_f32_e32 v81, v81
	v_exp_f32_e32 v82, v82
	v_fma_f32 v83, v83, s30, -v225
	v_exp_f32_e32 v83, v83
	v_fma_f32 v84, v84, s30, -v225
	v_add_f32_e32 v214, 0, v80
	v_exp_f32_e32 v84, v84
	v_fma_f32 v85, v85, s30, -v225
	v_add_f32_e32 v214, v81, v214
	v_exp_f32_e32 v85, v85
	v_fma_f32 v86, v86, s30, -v225
	v_add_f32_e32 v214, v82, v214
	v_exp_f32_e32 v86, v86
	v_fma_f32 v87, v87, s30, -v225
	v_add_f32_e32 v214, v83, v214
	v_exp_f32_e32 v87, v87
	v_fma_f32 v88, v88, s30, -v225
	v_add_f32_e32 v214, v84, v214
	v_exp_f32_e32 v88, v88
	v_fma_f32 v89, v89, s30, -v225
	v_add_f32_e32 v214, v85, v214
	v_exp_f32_e32 v89, v89
	v_fma_f32 v90, v90, s30, -v225
	v_add_f32_e32 v214, v86, v214
	v_exp_f32_e32 v90, v90
	v_fma_f32 v91, v91, s30, -v225
	v_add_f32_e32 v214, v87, v214
	v_exp_f32_e32 v91, v91
	v_fma_f32 v92, v92, s30, -v225
	v_add_f32_e32 v214, v88, v214
	v_exp_f32_e32 v92, v92
	v_fma_f32 v93, v93, s30, -v225
	v_add_f32_e32 v214, v89, v214
	v_exp_f32_e32 v93, v93
	v_fma_f32 v94, v94, s30, -v225
	v_add_f32_e32 v214, v90, v214
	v_exp_f32_e32 v94, v94
	v_fma_f32 v95, v95, s30, -v225
	v_add_f32_e32 v214, v91, v214
	v_exp_f32_e32 v95, v95
	v_fma_f32 v64, v64, s30, -v225
	v_add_f32_e32 v214, v92, v214
	v_exp_f32_e32 v64, v64
	v_fma_f32 v65, v65, s30, -v225
	v_add_f32_e32 v214, v93, v214
	v_exp_f32_e32 v65, v65
	v_fma_f32 v66, v66, s30, -v225
	v_add_f32_e32 v214, v94, v214
	v_exp_f32_e32 v66, v66
	v_fma_f32 v67, v67, s30, -v225
	v_add_f32_e32 v214, v95, v214
	v_exp_f32_e32 v67, v67
	v_fma_f32 v68, v68, s30, -v225
	v_add_f32_e32 v214, v64, v214
	v_exp_f32_e32 v68, v68
	v_fma_f32 v69, v69, s30, -v225
	v_add_f32_e32 v214, v65, v214
	v_exp_f32_e32 v69, v69
	v_fma_f32 v70, v70, s30, -v225
	v_add_f32_e32 v214, v66, v214
	v_exp_f32_e32 v70, v70
	v_fma_f32 v71, v71, s30, -v225
	v_add_f32_e32 v214, v67, v214
	v_exp_f32_e32 v71, v71
	v_fma_f32 v72, v72, s30, -v225
	v_add_f32_e32 v214, v68, v214
	v_exp_f32_e32 v72, v72
	v_fma_f32 v73, v73, s30, -v225
	v_add_f32_e32 v214, v69, v214
	v_exp_f32_e32 v73, v73
	v_fma_f32 v74, v74, s30, -v225
	v_add_f32_e32 v214, v70, v214
	v_exp_f32_e32 v74, v74
	v_fma_f32 v75, v75, s30, -v225
	v_add_f32_e32 v214, v71, v214
	v_exp_f32_e32 v75, v75
	v_fma_f32 v76, v76, s30, -v225
	v_add_f32_e32 v214, v72, v214
	v_exp_f32_e32 v76, v76
	v_fma_f32 v77, v77, s30, -v225
	v_add_f32_e32 v214, v73, v214
	v_exp_f32_e32 v77, v77
	v_fma_f32 v78, v78, s30, -v225
	v_add_f32_e32 v214, v74, v214
	v_exp_f32_e32 v78, v78
	v_fma_f32 v79, v79, s30, -v225
	v_add_f32_e32 v214, v75, v214
	v_exp_f32_e32 v79, v79
	v_fma_f32 v48, v48, s30, -v225
	v_add_f32_e32 v214, v76, v214
	v_exp_f32_e32 v48, v48
	v_fma_f32 v49, v49, s30, -v225
	v_add_f32_e32 v214, v77, v214
	v_exp_f32_e32 v49, v49
	v_fma_f32 v50, v50, s30, -v225
	v_add_f32_e32 v214, v78, v214
	v_exp_f32_e32 v50, v50
	v_fma_f32 v51, v51, s30, -v225
	v_add_f32_e32 v214, v79, v214
	v_exp_f32_e32 v51, v51
	v_fma_f32 v52, v52, s30, -v225
	v_add_f32_e32 v214, v48, v214
	v_exp_f32_e32 v52, v52
	v_fma_f32 v53, v53, s30, -v225
	v_add_f32_e32 v214, v49, v214
	v_exp_f32_e32 v53, v53
	v_fma_f32 v54, v54, s30, -v225
	v_add_f32_e32 v214, v50, v214
	v_exp_f32_e32 v54, v54
	v_fma_f32 v55, v55, s30, -v225
	v_add_f32_e32 v214, v51, v214
	v_exp_f32_e32 v55, v55
	v_fma_f32 v56, v56, s30, -v225
	v_add_f32_e32 v214, v52, v214
	v_exp_f32_e32 v56, v56
	v_fma_f32 v57, v57, s30, -v225
	v_add_f32_e32 v214, v53, v214
	v_exp_f32_e32 v57, v57
	v_fma_f32 v58, v58, s30, -v225
	v_add_f32_e32 v214, v54, v214
	v_exp_f32_e32 v58, v58
	v_fma_f32 v59, v59, s30, -v225
	v_add_f32_e32 v214, v55, v214
	v_exp_f32_e32 v59, v59
	v_fma_f32 v60, v60, s30, -v225
	v_add_f32_e32 v214, v56, v214
	v_exp_f32_e32 v60, v60
	v_fma_f32 v61, v61, s30, -v225
	v_add_f32_e32 v214, v57, v214
	v_exp_f32_e32 v61, v61
	v_fma_f32 v62, v62, s30, -v225
	v_add_f32_e32 v214, v58, v214
	v_exp_f32_e32 v62, v62
	v_fma_f32 v63, v63, s30, -v225
	v_add_f32_e32 v214, v59, v214
	v_exp_f32_e32 v63, v63
	v_fma_f32 v32, v32, s30, -v225
	v_add_f32_e32 v214, v60, v214
; #define LAS __attribute__((address_space(3)))
; __device__ __forceinline__ unsigned pk2(float lo, float hi) { unsigned r; asm volatile("v_cvt_pk_bf16_f32 %0, %1, %2" : "=v"(r) : "v"(lo), "v"(hi)); return r; }
; __device__ void attn_item(const Params& p, int l, int item, LAS unsigned char* lds) {
;     ...
;             for (int r = 0; r < 16; ++r) { const float e = __builtin_amdgcn_exp2f(fmaf(st[kt][r], LOG2E, -mnew)); st[kt][r] = e; rs += e; }
;         rs += __shfl_xor(rs, 32);
;         lrun = lrun * alpha + rs; mrun = mnew;
; #pragma unroll
;         for (int dt = 0; dt < 2; ++dt)
; #pragma unroll
;             for (int r = 0; r < 16; ++r) ot[dt][r] *= alpha;
; #pragma unroll
;         for (int kt = 0; kt < 4; ++kt)
; #pragma unroll
;             for (int s = 0; s < 2; ++s) {
;                 __builtin_amdgcn_sched_barrier(0);
;                 u32x4 pw; pw.x = pk2(st[kt][8 * s + 0], st[kt][8 * s + 1]); pw.y = pk2(st[kt][8 * s + 2], st[kt][8 * s + 3]);
;                 pw.z = pk2(st[kt][8 * s + 4], st[kt][8 * s + 5]); pw.w = pk2(st[kt][8 * s + 6], st[kt][8 * s + 7]);
;                 const bf16x8 pf = __builtin_bit_cast(bf16x8, pw);
; #pragma unroll
;                 for (int dt = 0; dt < 2; ++dt) {
;                     const LAS unsigned char* va = Vt + (32 * dt + l31) * VPITCH + (32 * kt + 16 * s + 4 * hi) * 2;
;                     const u32x2 a0 = *(const LAS u32x2*)va, a1 = *(const LAS u32x2*)(va + 16);
;                     u32x4 aw; aw.x = a0.x; aw.y = a0.y; aw.z = a1.x; aw.w = a1.y;
;                     ot[dt] = __builtin_amdgcn_mfma_f32_32x32x16_bf16(__builtin_bit_cast(bf16x8, aw), pf, ot[dt], 0, 0, 0);
;                 }
;             }
	v_exp_f32_e32 v215, v32
	v_fma_f32 v33, v33, s30, -v225
	v_add_f32_e32 v32, v61, v214
	v_exp_f32_e32 v214, v33
	v_fma_f32 v33, v34, s30, -v225
	v_add_f32_e32 v32, v62, v32
	v_exp_f32_e32 v224, v33
	v_fma_f32 v33, v35, s30, -v225
	v_add_f32_e32 v32, v63, v32
	v_exp_f32_e32 v226, v33
	v_fma_f32 v33, v36, s30, -v225
	v_add_f32_e32 v32, v215, v32
	v_exp_f32_e32 v227, v33
	v_fma_f32 v33, v37, s30, -v225
	v_add_f32_e32 v32, v214, v32
	v_exp_f32_e32 v228, v33
	v_fma_f32 v33, v38, s30, -v225
	v_add_f32_e32 v32, v224, v32
	v_exp_f32_e32 v229, v33
	v_fma_f32 v33, v39, s30, -v225
	v_add_f32_e32 v32, v226, v32
	v_exp_f32_e32 v230, v33
	v_fma_f32 v33, v40, s30, -v225
	v_add_f32_e32 v32, v227, v32
	v_exp_f32_e32 v231, v33
	v_fma_f32 v33, v41, s30, -v225
	v_add_f32_e32 v32, v228, v32
	v_exp_f32_e32 v232, v33
	v_fma_f32 v33, v42, s30, -v225
	v_add_f32_e32 v32, v229, v32
	v_exp_f32_e32 v42, v33
	v_fma_f32 v33, v43, s30, -v225
	v_add_f32_e32 v32, v230, v32
	v_exp_f32_e32 v43, v33
	v_fma_f32 v33, v44, s30, -v225
	v_add_f32_e32 v32, v231, v32
	v_exp_f32_e32 v44, v33
	v_fma_f32 v33, v45, s30, -v225
	v_add_f32_e32 v32, v232, v32
	v_exp_f32_e32 v45, v33
	v_fma_f32 v33, v46, s30, -v225
	v_add_f32_e32 v32, v42, v32
	v_exp_f32_e32 v46, v33
	v_fma_f32 v33, v47, s30, -v225
	v_add_f32_e32 v32, v43, v32
	v_exp_f32_e32 v47, v33
	v_add_f32_e32 v32, v44, v32
	v_add_f32_e32 v33, v45, v32
	v_add_f32_e32 v33, v46, v33
	v_add_f32_e32 v33, v47, v33
	ds_bpermute_b32 v34, v213, v33
	v_exp_f32_e32 v32, v212
	s_nop 0
	v_pk_mul_f32 v[30:31], v[30:31], v[32:33] op_sel_hi:[1,0]
	v_pk_mul_f32 v[28:29], v[28:29], v[32:33] op_sel_hi:[1,0]
	v_pk_mul_f32 v[26:27], v[26:27], v[32:33] op_sel_hi:[1,0]
	v_pk_mul_f32 v[24:25], v[24:25], v[32:33] op_sel_hi:[1,0]
	v_pk_mul_f32 v[22:23], v[22:23], v[32:33] op_sel_hi:[1,0]
	v_pk_mul_f32 v[20:21], v[20:21], v[32:33] op_sel_hi:[1,0]
	v_pk_mul_f32 v[18:19], v[18:19], v[32:33] op_sel_hi:[1,0]
	v_pk_mul_f32 v[16:17], v[16:17], v[32:33] op_sel_hi:[1,0]
	v_pk_mul_f32 v[14:15], v[14:15], v[32:33] op_sel_hi:[1,0]
	v_pk_mul_f32 v[12:13], v[12:13], v[32:33] op_sel_hi:[1,0]
	v_pk_mul_f32 v[10:11], v[10:11], v[32:33] op_sel_hi:[1,0]
	v_pk_mul_f32 v[8:9], v[8:9], v[32:33] op_sel_hi:[1,0]
	v_pk_mul_f32 v[6:7], v[6:7], v[32:33] op_sel_hi:[1,0]
	v_pk_mul_f32 v[4:5], v[4:5], v[32:33] op_sel_hi:[1,0]
	v_pk_mul_f32 v[2:3], v[2:3], v[32:33] op_sel_hi:[1,0]
	v_pk_mul_f32 v[0:1], v[0:1], v[32:33] op_sel_hi:[1,0]
	s_waitcnt lgkmcnt(0)
	v_add_f32_e32 v33, v33, v34
	v_add_u32_e32 v212, 0x4800, v222
	v_add_u32_e32 v213, 0x6800, v222
	ds_read2_b64 v[34:37], v212 offset0:0 offset1:2
	ds_read2_b64 v[38:41], v213 offset0:64 offset1:66
	v_cvt_pk_bf16_f32 v80, v80, v81
	v_cvt_pk_bf16_f32 v81, v82, v83
	v_cvt_pk_bf16_f32 v82, v84, v85
	v_cvt_pk_bf16_f32 v83, v86, v87
	v_cvt_pk_bf16_f32 v84, v88, v89
	v_cvt_pk_bf16_f32 v85, v90, v91
	v_cvt_pk_bf16_f32 v86, v92, v93
	v_cvt_pk_bf16_f32 v87, v94, v95
	ds_read2_b64 v[88:91], v212 offset0:4 offset1:6
	ds_read2_b64 v[92:95], v213 offset0:68 offset1:70
	v_cvt_pk_bf16_f32 v64, v64, v65
	v_cvt_pk_bf16_f32 v65, v66, v67
	v_cvt_pk_bf16_f32 v66, v68, v69
	v_cvt_pk_bf16_f32 v67, v70, v71
	v_cvt_pk_bf16_f32 v68, v72, v73
	v_cvt_pk_bf16_f32 v69, v74, v75
	v_cvt_pk_bf16_f32 v70, v76, v77
	v_cvt_pk_bf16_f32 v71, v78, v79
	ds_read2_b64 v[72:75], v212 offset0:8 offset1:10
	ds_read2_b64 v[76:79], v213 offset0:72 offset1:74
	s_waitcnt lgkmcnt(5)
	v_mfma_f32_32x32x16_bf16 v[16:31], v[34:37], v[80:83], v[16:31]
	s_waitcnt lgkmcnt(4)
	v_mfma_f32_32x32x16_bf16 v[0:15], v[38:41], v[80:83], v[0:15]
	ds_read2_b64 v[34:37], v212 offset0:12 offset1:14
	ds_read2_b64 v[38:41], v213 offset0:76 offset1:78
	v_cvt_pk_bf16_f32 v48, v48, v49
	v_cvt_pk_bf16_f32 v49, v50, v51
	v_cvt_pk_bf16_f32 v50, v52, v53
	v_cvt_pk_bf16_f32 v51, v54, v55
	v_cvt_pk_bf16_f32 v52, v56, v57
	v_cvt_pk_bf16_f32 v53, v58, v59
	v_cvt_pk_bf16_f32 v54, v60, v61
	v_cvt_pk_bf16_f32 v55, v62, v63
	s_waitcnt lgkmcnt(5)
	v_mfma_f32_32x32x16_bf16 v[16:31], v[88:91], v[84:87], v[16:31]
	s_waitcnt lgkmcnt(4)
	v_mfma_f32_32x32x16_bf16 v[0:15], v[92:95], v[84:87], v[0:15]
	ds_read2_b64 v[88:91], v212 offset0:16 offset1:18
	ds_read2_b64 v[92:95], v213 offset0:80 offset1:82
	v_cvt_pk_bf16_f32 v56, v215, v214
	v_cvt_pk_bf16_f32 v57, v224, v226
	v_cvt_pk_bf16_f32 v58, v227, v228
	v_cvt_pk_bf16_f32 v59, v229, v230
	v_cvt_pk_bf16_f32 v60, v231, v232
	v_cvt_pk_bf16_f32 v61, v42, v43
	v_cvt_pk_bf16_f32 v62, v44, v45
	v_cvt_pk_bf16_f32 v63, v46, v47
	s_waitcnt lgkmcnt(5)
	v_mfma_f32_32x32x16_bf16 v[16:31], v[72:75], v[64:67], v[16:31]
	s_waitcnt lgkmcnt(4)
	v_mfma_f32_32x32x16_bf16 v[0:15], v[76:79], v[64:67], v[0:15]
	ds_read2_b64 v[72:75], v212 offset0:20 offset1:22
	ds_read2_b64 v[76:79], v213 offset0:84 offset1:86
	s_waitcnt lgkmcnt(5)
	v_mfma_f32_32x32x16_bf16 v[16:31], v[34:37], v[68:71], v[16:31]
	s_waitcnt lgkmcnt(4)
	v_mfma_f32_32x32x16_bf16 v[0:15], v[38:41], v[68:71], v[0:15]
	ds_read2_b64 v[34:37], v212 offset0:24 offset1:26
	ds_read2_b64 v[38:41], v213 offset0:88 offset1:90
	s_waitcnt lgkmcnt(5)
	v_mfma_f32_32x32x16_bf16 v[16:31], v[88:91], v[48:51], v[16:31]
	s_waitcnt lgkmcnt(4)
	v_mfma_f32_32x32x16_bf16 v[0:15], v[92:95], v[48:51], v[0:15]
	ds_read2_b64 v[88:91], v212 offset0:28 offset1:30
	ds_read2_b64 v[92:95], v213 offset0:92 offset1:94
	s_waitcnt lgkmcnt(5)
	v_mfma_f32_32x32x16_bf16 v[16:31], v[72:75], v[52:55], v[16:31]
	s_waitcnt lgkmcnt(4)
	v_mfma_f32_32x32x16_bf16 v[0:15], v[76:79], v[52:55], v[0:15]
	v_fmac_f32_e32 v33, v223, v32
	s_andn2_b64 vcc, exec, s[24:25]
	s_waitcnt lgkmcnt(3)
	v_mfma_f32_32x32x16_bf16 v[16:31], v[34:37], v[56:59], v[16:31]
	s_waitcnt lgkmcnt(2)
	v_mfma_f32_32x32x16_bf16 v[0:15], v[38:41], v[56:59], v[0:15]
	s_waitcnt lgkmcnt(1)
	v_mfma_f32_32x32x16_bf16 v[16:31], v[88:91], v[60:63], v[16:31]
	s_waitcnt lgkmcnt(0)
	v_mfma_f32_32x32x16_bf16 v[0:15], v[92:95], v[60:63], v[0:15]
	s_cbranch_vccz .LBB0_35
	v_mov_b32_e32 v224, v225
	v_mov_b32_e32 v223, v33
	s_mov_b32 s34, s35
	s_branch .LBB0_182
